# grid barrier leader path: L1 invalidate no longer waited for before the cross-XCD arrival; on top of the sample-unit entry change
# speedup vs baseline: 1.0025x; 1.0019x over previous
; __device__ __forceinline__ unsigned xb_add(unsigned* p, unsigned v) { return __hip_atomic_fetch_add(p, v, __ATOMIC_RELAXED, __HIP_MEMORY_SCOPE_AGENT); }
; __device__ __forceinline__ void xcd_barrier_t0(const XcdBarrier& b, const bool wb = true) {
;     ...
;         if (old + 1u == (gen + 1u) * nloc) {
;             if (wb) __builtin_amdgcn_fence(__ATOMIC_RELEASE, "agent");
;             asm volatile("buffer_inv sc1" ::: "memory");
;             asm volatile("s_waitcnt vmcnt(0)" ::: "memory");
;             const unsigned og = xb_add(&bar[XB_TOP], 1u);
;             const unsigned tg = og / nx;
;             if (og + 1u == (tg + 1u) * nx) xb_add(&bar[XB_TOPGEN], 1u);
.LBB0_97:
	s_andn2_saveexec_b64 s[8:9], s[8:9]
	s_cbranch_execz .LBB0_117
	s_mov_b64 s[8:9], exec
	buffer_wbl2 sc1
	s_waitcnt vmcnt(0) lgkmcnt(0)
	buffer_inv sc1
	v_mbcnt_lo_u32_b32 v2, s8, 0
	v_mbcnt_hi_u32_b32 v2, s9, v2
	v_cmp_eq_u32_e32 vcc, 0, v2
	s_and_saveexec_b64 s[10:11], vcc
	s_cbranch_execz .LBB0_100
	s_bcnt1_i32_b64 s8, s[8:9]
	v_mov_b32_e32 v3, 0x7000
	v_mov_b32_e32 v4, s8
	global_atomic_add v3, v3, v4, s[4:5] offset:1024 sc0

; __device__ __forceinline__ unsigned xb_add(unsigned* p, unsigned v) { return __hip_atomic_fetch_add(p, v, __ATOMIC_RELAXED, __HIP_MEMORY_SCOPE_AGENT); }
; __device__ __forceinline__ void xcd_barrier_t0(const XcdBarrier& b, const bool wb = true) {
;     ...
;         if (old + 1u == (gen + 1u) * nloc) {
;             if (wb) __builtin_amdgcn_fence(__ATOMIC_RELEASE, "agent");
;             asm volatile("buffer_inv sc1" ::: "memory");
;             asm volatile("s_waitcnt vmcnt(0)" ::: "memory");
;             const unsigned og = xb_add(&bar[XB_TOP], 1u);
;             const unsigned tg = og / nx;
;             if (og + 1u == (tg + 1u) * nx) xb_add(&bar[XB_TOPGEN], 1u);
.LBB0_594:
	s_mov_b64 s[14:15], exec
	buffer_inv sc1
	v_mbcnt_lo_u32_b32 v0, s14, 0
	v_mbcnt_hi_u32_b32 v0, s15, v0
	v_cmp_eq_u32_e32 vcc, 0, v0
	s_and_saveexec_b64 s[16:17], vcc
	s_cbranch_execz .LBB0_596
	s_bcnt1_i32_b64 s0, s[14:15]
	v_mov_b32_e32 v3, s0
	v_readlane_b32 s0, v251, 35
	v_readlane_b32 s1, v251, 36
	s_nop 4
	global_atomic_add v3, v1, v3, s[0:1] sc0

; __device__ __forceinline__ unsigned xb_add(unsigned* p, unsigned v) { return __hip_atomic_fetch_add(p, v, __ATOMIC_RELAXED, __HIP_MEMORY_SCOPE_AGENT); }
; __device__ __forceinline__ void xcd_barrier_t0(const XcdBarrier& b, const bool wb = true) {
;     ...
;         if (old + 1u == (gen + 1u) * nloc) {
;             if (wb) __builtin_amdgcn_fence(__ATOMIC_RELEASE, "agent");
;             asm volatile("buffer_inv sc1" ::: "memory");
;             asm volatile("s_waitcnt vmcnt(0)" ::: "memory");
;             const unsigned og = xb_add(&bar[XB_TOP], 1u);
;             const unsigned tg = og / nx;
;             if (og + 1u == (tg + 1u) * nx) xb_add(&bar[XB_TOPGEN], 1u);
.LBB0_647:
	s_andn2_saveexec_b64 s[0:1], s[14:15]
	s_cbranch_execz .LBB0_667
	s_mov_b64 s[14:15], exec
	buffer_wbl2 sc1
	s_waitcnt vmcnt(0) lgkmcnt(0)
	buffer_inv sc1
	v_mbcnt_lo_u32_b32 v0, s14, 0
	v_mbcnt_hi_u32_b32 v0, s15, v0
	v_cmp_eq_u32_e32 vcc, 0, v0
	s_and_saveexec_b64 s[16:17], vcc
	s_cbranch_execz .LBB0_650
	s_bcnt1_i32_b64 s0, s[14:15]
	v_mov_b32_e32 v3, s0
	v_readlane_b32 s0, v251, 35
	v_readlane_b32 s1, v251, 36
	s_nop 4
	global_atomic_add v3, v1, v3, s[0:1] sc0

; __device__ __forceinline__ unsigned xb_add(unsigned* p, unsigned v) { return __hip_atomic_fetch_add(p, v, __ATOMIC_RELAXED, __HIP_MEMORY_SCOPE_AGENT); }
; __device__ __forceinline__ void xcd_barrier_t0(const XcdBarrier& b, const bool wb = true) {
;     ...
;         if (old + 1u == (gen + 1u) * nloc) {
;             if (wb) __builtin_amdgcn_fence(__ATOMIC_RELEASE, "agent");
;             asm volatile("buffer_inv sc1" ::: "memory");
;             asm volatile("s_waitcnt vmcnt(0)" ::: "memory");
;             const unsigned og = xb_add(&bar[XB_TOP], 1u);
;             const unsigned tg = og / nx;
;             if (og + 1u == (tg + 1u) * nx) xb_add(&bar[XB_TOPGEN], 1u);
.LBB0_769:
	s_andn2_saveexec_b64 s[14:15], s[14:15]
	s_cbranch_execz .LBB0_789
	s_mov_b64 s[16:17], exec
	buffer_wbl2 sc1
	s_waitcnt vmcnt(0) lgkmcnt(0)
	buffer_inv sc1
	v_mbcnt_lo_u32_b32 v3, s16, 0
	v_mbcnt_hi_u32_b32 v3, s17, v3
	v_cmp_eq_u32_e32 vcc, 0, v3
	s_and_saveexec_b64 s[18:19], vcc
	s_cbranch_execz .LBB0_772
	s_bcnt1_i32_b64 s0, s[16:17]
	v_mov_b32_e32 v4, s0
	v_readlane_b32 s0, v251, 35
	v_readlane_b32 s1, v251, 36
	s_nop 4
	global_atomic_add v4, v1, v4, s[0:1] sc0

; __device__ __forceinline__ unsigned xb_add(unsigned* p, unsigned v) { return __hip_atomic_fetch_add(p, v, __ATOMIC_RELAXED, __HIP_MEMORY_SCOPE_AGENT); }
; __device__ __forceinline__ void xcd_barrier_t0(const XcdBarrier& b, const bool wb = true) {
;     ...
;         if (old + 1u == (gen + 1u) * nloc) {
;             if (wb) __builtin_amdgcn_fence(__ATOMIC_RELEASE, "agent");
;             asm volatile("buffer_inv sc1" ::: "memory");
;             asm volatile("s_waitcnt vmcnt(0)" ::: "memory");
;             const unsigned og = xb_add(&bar[XB_TOP], 1u);
;             const unsigned tg = og / nx;
;             if (og + 1u == (tg + 1u) * nx) xb_add(&bar[XB_TOPGEN], 1u);
.LBB0_1798:
	s_mov_b64 s[14:15], exec
	buffer_wbl2 sc1
	s_waitcnt vmcnt(0) lgkmcnt(0)
	buffer_inv sc1
	v_mbcnt_lo_u32_b32 v0, s14, 0
	v_mbcnt_hi_u32_b32 v0, s15, v0
	v_cmp_eq_u32_e32 vcc, 0, v0
	s_and_saveexec_b64 s[16:17], vcc
	s_cbranch_execz .LBB0_1800
	s_bcnt1_i32_b64 s0, s[14:15]
	v_mov_b32_e32 v3, s0
	v_readlane_b32 s0, v251, 35
	v_readlane_b32 s1, v251, 36
	s_nop 4
	global_atomic_add v3, v1, v3, s[0:1] sc0
